# v9 plus strength-reduced K/V global-load address computation in MLA tile loop
# baseline (speedup 1.0000x reference)
; #define LAS __attribute__((address_space(3)))
; template <int DQK, int MODE>
; DEVI void attn_item(LAS unsigned char* lds, const bf16_t* Qh, int qs, const bf16_t* Kh, int ks_, const bf16_t* Vh, int vs, bf16_t* Oh, int os,
;                     float* lse, int lses, int i0, int dil, int res) {
;     ...
;     { const bf16_t* qrow = Qh + (size_t)(res + dil * qidx) * qs;
; #pragma unroll
;       for (int k = 0; k < DQK / 16; ++k) qf[k] = *(const bf16x8*)(qrow + 16 * k + 8 * hh);
; #pragma unroll
;       for (int k = 0; k < DQK / 16; ++k) asm volatile("" : "+v"(qf[k]));
;     }
;     const int kbase = MODE ? (i0 - 128) : 0;
;     const int j0 = (MODE && kbase < 0) ? 2 : 0;
;     const int j1 = MODE ? 6 : (i0 / 64 + 4);
;     f32x16 O[4];
; #pragma unroll
;     for (int c = 0; c < 4; ++c)
; #pragma unroll
;         for (int j = 0; j < 16; ++j) O[c][j] = 0.f;
;     float mrun = -1e30f, lrun = 0.f;
;     u32x4 kreg[C::NKC], vreg[2];
;     u32x4 pk[4];
; #pragma unroll
;     for (int i = 0; i < 4; ++i) pk[i] = (u32x4){0u, 0u, 0u, 0u};
;     auto gload = [&](int jt) {
;         const int kb0 = kbase + 64 * jt;
; #pragma unroll
;         for (int u = 0; u < C::NKC; ++u) { const int id = tid + NT * u, row = id / (DQK / 8), cc = id % (DQK / 8);
;             kreg[u] = *(const u32x4*)(Kh + (size_t)(res + dil * (kb0 + row)) * ks_ + cc * 8); }
; #pragma unroll
;         for (int u = 0; u < 2; ++u) { const int id = tid + NT * u, row = id >> 4, cc = id & 15;
;             vreg[u] = *(const u32x4*)(Vh + (size_t)(res + dil * (kb0 + row)) * vs + cc * 8); }
;     };
;     auto lstore = [&](int kbi, int vbi) {
;         LAS unsigned char* kb_ = lds + kbi * C::KB; LAS unsigned char* vb_ = lds + C::VOFF + vbi * C::VB;
; #pragma unroll
;         for (int u = 0; u < C::NKC; ++u) { const int id = tid + NT * u, row = id / (DQK / 8), cc = id % (DQK / 8);
;             *(LAS u32x4*)(kb_ + row * C::KSTR + cc * 16) = kreg[u]; }
; #pragma unroll
;         for (int u = 0; u < 2; ++u) { const int id = tid + NT * u, row = id >> 4, cc = id & 15;
; DEVI void emix(LAS unsigned char* lds, const Params& P) {
;     ...
;         const int head = slot[0], n = slot[1];
;         __syncthreads();
;         if (head < 0) break;
;         const int qb = 63 - n;
;         attn_item<192, 0>(lds, Q + head * 192, 1536, Km + head * 192, 1536, kv + head * 256 + 128, 2048, mix + head * 128, 2048, nullptr, 0, qb * 256, 1, 0);
.LBB0_1091:
	s_or_b64 exec, exec, s[14:15]
	s_waitcnt lgkmcnt(0)
	s_barrier
	ds_read_b64 v[2:3], v192
	s_waitcnt lgkmcnt(0)
	s_barrier
	v_readfirstlane_b32 s31, v2
	v_readfirstlane_b32 s14, v3
	s_cmp_lt_i32 s31, 0
	s_cbranch_scc1 .LBB0_1108
	s_mul_i32 s0, s31, 0xc0
	s_lshl_b64 s[16:17], s[0:1], 1
	s_add_u32 s50, s4, s16
	s_addc_u32 s51, s5, s17
	s_add_u32 s16, s6, s16
	s_addc_u32 s17, s7, s17
	s_lshl_b32 s0, s31, 8
	s_lshl_b64 s[72:73], s[0:1], 1
	v_readlane_b32 s76, v239, 0
	v_readlane_b32 s77, v239, 1
	s_add_u32 s0, s76, s72
	v_readlane_b32 s80, v239, 4
	s_addc_u32 s15, s77, s73
	v_readlane_b32 s81, v239, 5
	s_add_u32 s80, s0, 0x20ec4500
	s_addc_u32 s81, s15, 0
	s_lshl_b32 s0, s14, 8
	s_waitcnt vmcnt(17)
	v_mov_b32_e32 v22, v196
	s_sub_i32 s0, 0x3f00, s0
	v_mov_b64_e32 v[2:3], s[50:51]
	v_ashrrev_i32_e32 v23, 6, v22
	v_and_b32_e32 v14, 31, v22
	v_lshl_add_u32 v202, v23, 5, s0
	v_bfe_u32 v194, v22, 5, 1
	v_or_b32_e32 v180, v202, v14
	v_mad_i64_i32 v[4:5], s[14:15], v180, s27, v[2:3]
	v_lshlrev_b32_e32 v2, 4, v194
	v_mov_b32_e32 v3, v1
	v_lshl_add_u64 v[4:5], v[4:5], 0, v[2:3]
	global_load_dwordx4 v[112:115], v[4:5], off
	global_load_dwordx4 v[116:119], v[4:5], off offset:32
	global_load_dwordx4 v[120:123], v[4:5], off offset:64
	global_load_dwordx4 v[124:127], v[4:5], off offset:96
	global_load_dwordx4 v[128:131], v[4:5], off offset:128
	global_load_dwordx4 v[132:135], v[4:5], off offset:160
	global_load_dwordx4 v[136:139], v[4:5], off offset:192
	global_load_dwordx4 v[140:143], v[4:5], off offset:224
	global_load_dwordx4 v[144:147], v[4:5], off offset:256
	global_load_dwordx4 v[148:151], v[4:5], off offset:288
	global_load_dwordx4 v[152:155], v[4:5], off offset:320
	global_load_dwordx4 v[156:159], v[4:5], off offset:352
	v_mul_hi_i32 v0, v22, s28
	s_waitcnt vmcnt(28)
	v_add_u32_e32 v24, 0x200, v22
	v_add_u32_e32 v7, 0x400, v22
	v_ashrrev_i32_e32 v4, 4, v22
	v_lshlrev_b32_e32 v3, 3, v22
	v_lshrrev_b32_e32 v6, 31, v0
	v_ashrrev_i32_e32 v0, 2, v0
	v_mul_hi_i32 v8, v24, s28
	v_mul_hi_i32 v9, v7, s28
	v_ashrrev_i32_e32 v5, 31, v4
	v_and_b32_e32 v10, 0x78, v3
	v_add_u32_e32 v3, v0, v6
	v_lshrrev_b32_e32 v6, 31, v8
	v_ashrrev_i32_e32 v8, 2, v8
	v_lshrrev_b32_e32 v11, 31, v9
	v_ashrrev_i32_e32 v9, 2, v9
	v_lshlrev_b64 v[12:13], 12, v[4:5]
	v_lshlrev_b32_e32 v0, 1, v10
	v_mul_lo_u32 v10, v3, 24
	v_add_u32_e32 v5, v8, v6
	v_add_u32_e32 v15, v9, v11
	v_sub_u32_e32 v25, v22, v10
	v_mul_lo_u32 v10, v5, 24
	v_mul_lo_u32 v11, v15, 24
	v_mov_b64_e32 v[8:9], s[16:17]
	v_lshlrev_b32_e32 v6, 3, v25
	v_sub_u32_e32 v26, v24, v10
	v_sub_u32_e32 v27, v7, v11
	v_mad_i64_i32 v[16:17], s[14:15], v3, s27, v[8:9]
	v_mad_i64_i32 v[18:19], s[14:15], v5, s27, v[8:9]
	v_mad_i64_i32 v[20:21], s[14:15], v15, s27, v[8:9]
	v_ashrrev_i32_e32 v7, 31, v6
	v_lshlrev_b32_e32 v8, 3, v26
	v_lshlrev_b32_e32 v10, 3, v27
	v_lshl_add_u64 v[12:13], s[80:81], 0, v[12:13]
	v_lshl_add_u64 v[16:17], v[6:7], 1, v[16:17]
	v_ashrrev_i32_e32 v9, 31, v8
	v_ashrrev_i32_e32 v11, 31, v10
	v_lshl_add_u64 v[12:13], v[12:13], 0, v[0:1]
	v_lshl_add_u64 v[18:19], v[8:9], 1, v[18:19]
	v_lshl_add_u64 v[20:21], v[10:11], 1, v[20:21]
	v_readfirstlane_b32 s35, v23
	s_cmp_gt_i32 s35, 3
	v_readlane_b32 s82, v239, 6
	v_readlane_b32 s83, v239, 7
	v_mul_lo_u32 v206, v3, s29
	v_lshlrev_b32_e32 v209, 4, v25
	s_cselect_b64 s[14:15], -1, 0
	s_cmp_lt_i32 s35, 4
	v_bfe_u32 v199, v22, 2, 2
	s_waitcnt vmcnt(11)
	s_waitcnt vmcnt(10)
	s_waitcnt vmcnt(9)
	s_waitcnt vmcnt(8)
	s_waitcnt vmcnt(7)
	s_waitcnt vmcnt(6)
	s_waitcnt vmcnt(5)
	s_waitcnt vmcnt(4)
	s_waitcnt vmcnt(3)
	s_waitcnt vmcnt(2)
	s_waitcnt vmcnt(1)
	s_waitcnt vmcnt(0)
	global_load_dwordx4 v[160:163], v[16:17], off
	global_load_dwordx4 v[164:167], v[18:19], off
	global_load_dwordx4 v[168:171], v[20:21], off
	global_load_dwordx4 v[172:175], v[12:13], off
	v_ashrrev_i32_e32 v12, 4, v24
	v_ashrrev_i32_e32 v13, 31, v12
	v_lshlrev_b64 v[16:17], 12, v[12:13]
	v_lshl_add_u64 v[16:17], s[80:81], 0, v[16:17]
	v_lshl_add_u64 v[16:17], v[16:17], 0, v[0:1]
	global_load_dwordx4 v[176:179], v[16:17], off
	v_and_b32_e32 v13, 3, v22
	v_bfe_u32 v16, v22, 4, 1
	v_lshlrev_b32_e32 v17, 4, v22
	v_mul_lo_u32 v203, v4, s34
	v_and_b32_e32 v204, 0xf0, v17
	v_lshlrev_b32_e32 v200, 3, v13
	v_lshlrev_b32_e32 v201, 5, v16
	v_mul_lo_u32 v205, v12, s34
	v_mul_lo_u32 v207, v5, s29
	v_mul_lo_u32 v208, v15, s29
	v_add3_u32 v17, 0, v206, v209
	v_lshlrev_b32_e32 v210, 4, v26
	v_lshlrev_b32_e32 v211, 4, v27
	v_ashrrev_i32_e32 v181, 31, v180
	s_cselect_b64 s[82:83], -1, 0
	s_cmpk_lt_i32 s0, 0xff01
	v_lshlrev_b32_e32 v195, 2, v194
	v_readlane_b32 s78, v239, 2
	v_readlane_b32 s79, v239, 3
	v_add3_u32 v13, 0, v203, v204
	v_add3_u32 v16, 0, v205, v204
	v_add3_u32 v18, 0, v207, v210
	v_add3_u32 v19, 0, v208, v211
	s_waitcnt vmcnt(4)
	ds_write_b128 v17, v[160:163]
	s_waitcnt vmcnt(3)
	ds_write_b128 v18, v[164:167]
	s_waitcnt vmcnt(2)
	ds_write_b128 v19, v[168:171]
	s_waitcnt vmcnt(1)
	ds_write_b128 v13, v[172:175] offset:51200
	s_waitcnt vmcnt(0)
	ds_write_b128 v16, v[176:179] offset:51200
	s_waitcnt lgkmcnt(0)
	s_barrier
; template <int DQK, int MODE>
; DEVI void attn_item(LAS unsigned char* lds, const bf16_t* Qh, int qs, const bf16_t* Kh, int ks_, const bf16_t* Vh, int vs, bf16_t* Oh, int os,
;                     float* lse, int lses, int i0, int dil, int res) {
;     ...
;     f32x16 O[4];
; #pragma unroll
;     for (int c = 0; c < 4; ++c)
; #pragma unroll
;         for (int j = 0; j < 16; ++j) O[c][j] = 0.f;
;     float mrun = -1e30f, lrun = 0.f;
;     u32x4 kreg[C::NKC], vreg[2];
;     u32x4 pk[4];
; #pragma unroll
;     for (int i = 0; i < 4; ++i) pk[i] = (u32x4){0u, 0u, 0u, 0u};
;     auto gload = [&](int jt) {
;         const int kb0 = kbase + 64 * jt;
; #pragma unroll
;         for (int u = 0; u < C::NKC; ++u) { const int id = tid + NT * u, row = id / (DQK / 8), cc = id % (DQK / 8);
;             kreg[u] = *(const u32x4*)(Kh + (size_t)(res + dil * (kb0 + row)) * ks_ + cc * 8); }
; #pragma unroll
;         for (int u = 0; u < 2; ++u) { const int id = tid + NT * u, row = id >> 4, cc = id & 15;
;             vreg[u] = *(const u32x4*)(Vh + (size_t)(res + dil * (kb0 + row)) * vs + cc * 8); }
;     };
	s_cbranch_scc1 .LBB0_1109
	v_lshlrev_b32_e32 v212, 2, v194
	v_lshl_add_u64 v[188:189], s[80:81], 0, v[0:1]
	v_or_b32_e32 v0, v212, v199
	v_mad_u32_u24 v0, v0, s34, 0
	s_ashr_i32 s35, s0, 6
	v_add3_u32 v213, v0, v201, v200
	v_mul_u32_u24_e32 v0, 0x190, v14
	v_add_u32_e32 v218, 64, v15
	v_mov_b32_e32 v14, v1
	v_mov_b32_e32 v15, v1
	s_add_i32 s35, s35, 4
	v_lshl_add_u64 v[182:183], v[6:7], 1, s[16:17]
	v_lshl_add_u64 v[184:185], v[8:9], 1, s[16:17]
	v_lshl_add_u64 v[186:187], v[10:11], 1, s[16:17]
	v_add3_u32 v215, 0, v0, v2
	v_add_u32_e32 v216, 64, v12
	v_add_u32_e32 v217, 64, v4
	v_add_u32_e32 v219, 64, v5
	v_add_u32_e32 v220, 64, v3
	v_mov_b32_e32 v0, v1
	v_mov_b32_e32 v2, v1
	v_mov_b32_e32 v3, v1
	v_mov_b32_e32 v4, v1
	v_mov_b32_e32 v5, v1
	v_mov_b32_e32 v6, v1
	v_mov_b32_e32 v7, v1
	v_mov_b32_e32 v8, v1
	v_mov_b32_e32 v9, v1
	v_mov_b32_e32 v10, v1
	v_mov_b32_e32 v11, v1
	v_mov_b32_e32 v12, v1
	v_mov_b32_e32 v13, v1
	v_mov_b64_e32 v[30:31], v[14:15]
	v_mov_b64_e32 v[46:47], v[14:15]
	v_mov_b64_e32 v[62:63], v[14:15]
	v_mov_b64_e32 v[78:79], v[14:15]
	v_readlane_b32 s78, v240, 54
	v_or_b32_e32 v214, 31, v202
	s_max_i32 s49, s35, 1
	s_mov_b32 s50, 0
	s_mov_b64 s[80:81], 0
	v_mov_b32_e32 v190, 0xf149f2ca
	v_mov_b32_e32 v198, 0
	v_mov_b32_e32 v80, 0
	v_mov_b32_e32 v81, 0
	v_mov_b32_e32 v82, 0
	v_mov_b32_e32 v83, 0
	v_mov_b32_e32 v84, 0
	v_mov_b32_e32 v85, 0
	v_mov_b32_e32 v86, 0
	v_mov_b32_e32 v87, 0
	v_mov_b32_e32 v88, 0
	v_mov_b32_e32 v89, 0
	v_mov_b32_e32 v90, 0
	v_mov_b32_e32 v91, 0
	v_mov_b32_e32 v92, 0
	v_mov_b32_e32 v93, 0
	v_mov_b32_e32 v94, 0
	v_mov_b32_e32 v95, 0
	v_mov_b64_e32 v[28:29], v[12:13]
	v_mov_b64_e32 v[26:27], v[10:11]
	v_mov_b64_e32 v[24:25], v[8:9]
	v_mov_b64_e32 v[22:23], v[6:7]
	v_mov_b64_e32 v[20:21], v[4:5]
	v_mov_b64_e32 v[18:19], v[2:3]
	v_mov_b64_e32 v[16:17], v[0:1]
	v_mov_b64_e32 v[44:45], v[12:13]
	v_mov_b64_e32 v[42:43], v[10:11]
	v_mov_b64_e32 v[40:41], v[8:9]
	v_mov_b64_e32 v[38:39], v[6:7]
	v_mov_b64_e32 v[36:37], v[4:5]
	v_mov_b64_e32 v[34:35], v[2:3]
	v_mov_b64_e32 v[32:33], v[0:1]
	v_mov_b64_e32 v[60:61], v[12:13]
	v_mov_b64_e32 v[58:59], v[10:11]
	v_mov_b64_e32 v[56:57], v[8:9]
	v_mov_b64_e32 v[54:55], v[6:7]
	v_mov_b64_e32 v[52:53], v[4:5]
	v_mov_b64_e32 v[50:51], v[2:3]
	v_mov_b64_e32 v[48:49], v[0:1]
	v_mov_b64_e32 v[76:77], v[12:13]
	v_mov_b64_e32 v[74:75], v[10:11]
	v_mov_b64_e32 v[72:73], v[8:9]
	v_mov_b64_e32 v[70:71], v[6:7]
	v_mov_b64_e32 v[68:69], v[4:5]
	v_mov_b64_e32 v[66:67], v[2:3]
	v_mov_b64_e32 v[64:65], v[0:1]
	s_mov_b32 s51, 0
	s_mov_b32 s0, 0
	s_mov_b32 s72, 0
	v_readlane_b32 s79, v240, 55
	v_mad_i64_i32 v[242:243], s[16:17], v220, s27, v[182:183]
	v_mad_i64_i32 v[244:245], s[16:17], v219, s27, v[184:185]
	v_mad_i64_i32 v[246:247], s[16:17], v218, s27, v[186:187]
	v_ashrrev_i32_e32 v249, 31, v217
	v_mov_b32_e32 v248, v217
	v_lshlrev_b64 v[248:249], 12, v[248:249]
	v_lshl_add_u64 v[248:249], v[188:189], 0, v[248:249]
	v_ashrrev_i32_e32 v251, 31, v216
	v_mov_b32_e32 v250, v216
	v_lshlrev_b64 v[250:251], 12, v[250:251]
	v_lshl_add_u64 v[250:251], v[188:189], 0, v[250:251]
	s_branch .LBB0_1095

; template <int DQK, int MODE>
; DEVI void attn_item(LAS unsigned char* lds, const bf16_t* Qh, int qs, const bf16_t* Kh, int ks_, const bf16_t* Vh, int vs, bf16_t* Oh, int os,
;                     float* lse, int lses, int i0, int dil, int res) {
;     ...
;     auto gload = [&](int jt) {
;         const int kb0 = kbase + 64 * jt;
; #pragma unroll
;         for (int u = 0; u < C::NKC; ++u) { const int id = tid + NT * u, row = id / (DQK / 8), cc = id % (DQK / 8);
;             kreg[u] = *(const u32x4*)(Kh + (size_t)(res + dil * (kb0 + row)) * ks_ + cc * 8); }
; #pragma unroll
;         for (int u = 0; u < 2; ++u) { const int id = tid + NT * u, row = id >> 4, cc = id & 15;
;             vreg[u] = *(const u32x4*)(Vh + (size_t)(res + dil * (kb0 + row)) * vs + cc * 8); }
;     };
.LBB0_1095:
	s_add_i32 s72, s72, 1
	s_cmp_lt_i32 s72, s35
	s_cselect_b64 s[84:85], -1, 0
	s_cmp_ge_i32 s72, s35
	s_cbranch_scc1 .LBB0_1097
	s_mul_i32 s98, s50, 0xc00
	s_mov_b32 s99, 0
	s_lshl_b32 s100, s50, 12
	s_mov_b32 s101, 0
	v_lshl_add_u64 v[2:3], v[242:243], 0, s[98:99]
	v_lshl_add_u64 v[4:5], v[244:245], 0, s[98:99]
	global_load_dwordx4 v[160:163], v[2:3], off
	global_load_dwordx4 v[164:167], v[4:5], off
	v_lshl_add_u64 v[2:3], v[246:247], 0, s[98:99]
	v_lshl_add_u64 v[4:5], v[248:249], 0, s[100:101]
	global_load_dwordx4 v[168:171], v[2:3], off
	global_load_dwordx4 v[172:175], v[4:5], off
	v_lshl_add_u64 v[2:3], v[250:251], 0, s[100:101]
	global_load_dwordx4 v[176:179], v[2:3], off

; __global__ void __launch_bounds__(512, 2) hybrid_fwd(const Params P) {
	.amdhsa_kernel _Z10hybrid_fwd6Params
		.amdhsa_group_segment_fixed_size 0
		.amdhsa_private_segment_fixed_size 0
		.amdhsa_kernarg_size 2976
		.amdhsa_user_sgpr_count 2
		.amdhsa_user_sgpr_dispatch_ptr 0
		.amdhsa_user_sgpr_queue_ptr 0
		.amdhsa_user_sgpr_kernarg_segment_ptr 1
		.amdhsa_user_sgpr_dispatch_id 0
		.amdhsa_user_sgpr_kernarg_preload_length 0
		.amdhsa_user_sgpr_kernarg_preload_offset 0
		.amdhsa_user_sgpr_private_segment_size 0
		.amdhsa_uses_dynamic_stack 0
		.amdhsa_enable_private_segment 0
		.amdhsa_system_sgpr_workgroup_id_x 1
		.amdhsa_system_sgpr_workgroup_id_y 0
		.amdhsa_system_sgpr_workgroup_id_z 0
		.amdhsa_system_sgpr_workgroup_info 0
		.amdhsa_system_vgpr_workitem_id 2
		.amdhsa_next_free_vgpr 252
		.amdhsa_next_free_sgpr 102
		.amdhsa_accum_offset 252
		.amdhsa_reserve_vcc 1
		.amdhsa_float_round_mode_32 0
		.amdhsa_float_round_mode_16_64 0
		.amdhsa_float_denorm_mode_32 3
		.amdhsa_float_denorm_mode_16_64 3
		.amdhsa_dx10_clamp 1
		.amdhsa_ieee_mode 1
		.amdhsa_fp16_overflow 0
		.amdhsa_tg_split 0
		.amdhsa_exception_fp_ieee_invalid_op 0
		.amdhsa_exception_fp_denorm_src 0
		.amdhsa_exception_fp_ieee_div_zero 0
		.amdhsa_exception_fp_ieee_overflow 0
		.amdhsa_exception_fp_ieee_underflow 0
		.amdhsa_exception_fp_ieee_inexact 0
		.amdhsa_exception_int_div_zero 0
	.end_amdhsa_kernel

; __global__ void __launch_bounds__(512, 2) hybrid_fwd(const Params P) {
amdhsa.kernels:
  - .agpr_count:     0
    .args:
      - .offset:         0
        .size:           2720
        .value_kind:     by_value
      - .offset:         2720
        .size:           4
        .value_kind:     hidden_block_count_x
      - .offset:         2724
        .size:           4
        .value_kind:     hidden_block_count_y
      - .offset:         2728
        .size:           4
        .value_kind:     hidden_block_count_z
      - .offset:         2732
        .size:           2
        .value_kind:     hidden_group_size_x
      - .offset:         2734
        .size:           2
        .value_kind:     hidden_group_size_y
      - .offset:         2736
        .size:           2
        .value_kind:     hidden_group_size_z
      - .offset:         2738
        .size:           2
        .value_kind:     hidden_remainder_x
      - .offset:         2740
        .size:           2
        .value_kind:     hidden_remainder_y
      - .offset:         2742
        .size:           2
        .value_kind:     hidden_remainder_z
      - .offset:         2760
        .size:           8
        .value_kind:     hidden_global_offset_x
      - .offset:         2768
        .size:           8
        .value_kind:     hidden_global_offset_y
      - .offset:         2776
        .size:           8
        .value_kind:     hidden_global_offset_z
      - .offset:         2784
        .size:           2
        .value_kind:     hidden_grid_dims
      - .offset:         2808
        .size:           8
        .value_kind:     hidden_multigrid_sync_arg
      - .offset:         2840
        .size:           4
        .value_kind:     hidden_dynamic_lds_size
    .group_segment_fixed_size: 0
    .kernarg_segment_align: 8
    .kernarg_segment_size: 2976
    .language:       OpenCL C
    .language_version:
      - 2
      - 0
    .max_flat_workgroup_size: 512
    .name:           _Z10hybrid_fwd6Params
    .private_segment_fixed_size: 0
    .sgpr_count:     108
    .sgpr_spill_count: 350
    .symbol:         _Z10hybrid_fwd6Params.kd
    .uniform_work_group_size: 1
    .uses_dynamic_stack: false
    .vgpr_count:     252
    .vgpr_spill_count: 0
    .wavefront_size: 64
